# v100 + prep_run rope: 48 ds_swizzle(lane^4)+lgkmcnt(0) round trips replaced by two bank-masked v_mov_b32_dpp (row_shr:4 / row_shl:4) each
# speedup vs baseline: 1.0043x; 1.0043x over previous
.LBB0_473:
	s_or_b64 exec, exec, s[4:5]
	v_lshrrev_b32_e32 v9, 6, v9
	v_and_b32_e32 v17, 63, v26
	v_cndmask_b32_e64 v9, v17, v9, s[38:39]
	v_cvt_f32_ubyte0_e32 v9, v9
	v_mul_f32_e32 v17, v59, v9
	v_mul_f32_e32 v17, 0.15915494, v17
	v_cos_f32_e32 v51, v17
	v_sin_f32_e32 v56, v17
	v_mul_f32_e32 v17, v60, v9
	v_mul_f32_e32 v17, 0.15915494, v17
	v_cos_f32_e32 v49, v17
	v_sin_f32_e32 v50, v17
	v_mul_f32_e32 v17, v61, v9
	v_lshlrev_b32_e32 v53, 16, v47
	v_lshlrev_b32_e32 v52, 16, v46
	v_and_b32_e32 v47, 0xffff0000, v47
	v_and_b32_e32 v46, 0xffff0000, v46
	v_mul_f32_e32 v17, 0.15915494, v17
	v_mul_f32_e32 v9, v62, v9
	v_pk_mul_f32 v[54:55], v[46:47], v[46:47]
	v_cos_f32_e32 v25, v17
	v_sin_f32_e32 v48, v17
	v_mul_f32_e32 v17, 0.15915494, v9
	v_pk_fma_f32 v[54:55], v[52:53], v[52:53], v[54:55]
	v_cos_f32_e32 v9, v17
	v_sin_f32_e32 v21, v17
	v_add_f32_e32 v17, v54, v55
	v_mov_b32_e32 v55, v1
	s_nop 0
	v_add_f32_dpp v17, v17, v17 quad_perm:[1,0,3,2] row_mask:0xf bank_mask:0xf bound_ctrl:1
	s_nop 1
	v_add_f32_dpp v17, v17, v17 quad_perm:[2,3,0,1] row_mask:0xf bank_mask:0xf bound_ctrl:1
	s_nop 1
	v_add_f32_dpp v17, v17, v17 row_ror:4 row_mask:0xf bank_mask:0xf bound_ctrl:1
	s_nop 1
	v_add_f32_dpp v17, v17, v17 row_ror:8 row_mask:0xf bank_mask:0xf bound_ctrl:1
	v_fmamk_f32 v17, v17, 0x3c800000, v237
	v_rsq_f32_e32 v23, v17
	s_nop 0
	v_mul_f32_e32 v17, v23, v52
	v_mul_f32_e32 v17, v0, v17
	s_nop 1
	v_mov_b32_dpp v52, v17 row_shr:4 row_mask:0xf bank_mask:0xa
	v_mov_b32_dpp v52, v17 row_shl:4 row_mask:0xf bank_mask:0x5
	v_mul_f32_e32 v205, v23, v46
	s_waitcnt lgkmcnt(0)
	v_mul_f32_e32 v52, v56, v52
	v_cndmask_b32_e64 v52, v52, -v52, s[36:37]
	v_fmac_f32_e32 v52, v51, v17
	v_cndmask_b32_e64 v54, v52, v17, s[40:41]
	v_pk_mul_f32 v[54:55], v[54:55], v[204:205]
	s_nop 1
	v_mov_b32_dpp v17, v55 row_shr:4 row_mask:0xf bank_mask:0xa
	v_mov_b32_dpp v17, v55 row_shl:4 row_mask:0xf bank_mask:0x5
	v_mul_f32_e32 v205, v23, v53
	v_cndmask_b32_e64 v46, v54, v54, s[40:41]
	v_cndmask_b32_e64 v46, v46, v46, s[40:41]
	v_cndmask_b32_e64 v46, v46, v46, s[40:41]
	s_waitcnt lgkmcnt(0)
	v_mul_f32_e32 v17, v50, v17
	v_cndmask_b32_e64 v17, v17, -v17, s[36:37]
	v_fmac_f32_e32 v17, v49, v55
	v_cndmask_b32_e64 v17, v17, v55, s[40:41]
	v_pk_mov_b32 v[52:53], v[16:17], v[2:3] op_sel:[1,0]
	s_nop 0
	v_pk_mul_f32 v[52:53], v[52:53], v[204:205]
	s_nop 1
	v_mov_b32_dpp v54, v53 row_shr:4 row_mask:0xf bank_mask:0xa
	v_mov_b32_dpp v54, v53 row_shl:4 row_mask:0xf bank_mask:0x5
	v_mov_b32_e32 v17, v52
	v_cndmask_b32_e64 v17, v17, v52, s[40:41]
	v_mul_f32_e32 v205, v23, v47
	s_waitcnt lgkmcnt(0)
	v_mul_f32_e32 v54, v48, v54
	v_cndmask_b32_e64 v54, v54, -v54, s[36:37]
	v_fmac_f32_e32 v54, v25, v53
	v_cndmask_b32_e64 v52, v54, v53, s[40:41]
	v_mov_b32_e32 v53, v3
	v_pk_mul_f32 v[52:53], v[52:53], v[204:205]
	s_nop 1
	v_mov_b32_dpp v23, v53 row_shr:4 row_mask:0xf bank_mask:0xa
	v_mov_b32_dpp v23, v53 row_shl:4 row_mask:0xf bank_mask:0x5
	v_cndmask_b32_e64 v47, v52, v52, s[40:41]
	v_cndmask_b32_e64 v52, v17, v17, s[40:41]
	v_cvt_pk_bf16_f32 v46, v46, v52
	s_waitcnt lgkmcnt(0)
	v_mul_f32_e32 v23, v21, v23
	v_cndmask_b32_e64 v23, v23, -v23, s[36:37]
	v_fmac_f32_e32 v23, v9, v53
	v_cndmask_b32_e64 v17, v23, v53, s[40:41]
	v_mul_f32_e32 v17, 0x3e38aa3b, v17
	v_mov_b32_e32 v23, v161
	v_cvt_pk_bf16_f32 v47, v47, v17
	v_lshl_add_u64 v[52:53], v[34:35], 0, v[22:23]
	global_store_dwordx2 v[52:53], v[46:47], off offset:512
	v_lshlrev_b32_e32 v47, 16, v45
	v_lshlrev_b32_e32 v46, 16, v44
	v_and_b32_e32 v45, 0xffff0000, v45
	v_and_b32_e32 v44, 0xffff0000, v44
	v_pk_mul_f32 v[52:53], v[44:45], v[44:45]
	s_nop 0
	v_pk_fma_f32 v[52:53], v[46:47], v[46:47], v[52:53]
	s_nop 0
	v_add_f32_e32 v17, v52, v53
	v_mov_b32_e32 v53, v1
	s_nop 0
	v_add_f32_dpp v17, v17, v17 quad_perm:[1,0,3,2] row_mask:0xf bank_mask:0xf bound_ctrl:1
	s_nop 1
	v_add_f32_dpp v17, v17, v17 quad_perm:[2,3,0,1] row_mask:0xf bank_mask:0xf bound_ctrl:1
	s_nop 1
	v_add_f32_dpp v17, v17, v17 row_ror:4 row_mask:0xf bank_mask:0xf bound_ctrl:1
	s_nop 1
	v_add_f32_dpp v17, v17, v17 row_ror:8 row_mask:0xf bank_mask:0xf bound_ctrl:1
	v_fmamk_f32 v17, v17, 0x3c800000, v237
	v_rsq_f32_e32 v23, v17
	s_nop 0
	v_mul_f32_e32 v17, v23, v46
	v_mul_f32_e32 v17, v0, v17
	s_nop 1
	v_mov_b32_dpp v46, v17 row_shr:4 row_mask:0xf bank_mask:0xa
	v_mov_b32_dpp v46, v17 row_shl:4 row_mask:0xf bank_mask:0x5
	v_mul_f32_e32 v205, v23, v44
	s_waitcnt lgkmcnt(0)
	v_mul_f32_e32 v46, v56, v46
	v_cndmask_b32_e64 v46, v46, -v46, s[36:37]
	v_fmac_f32_e32 v46, v51, v17
	v_cndmask_b32_e64 v52, v46, v17, s[40:41]
	v_pk_mul_f32 v[52:53], v[52:53], v[204:205]
	s_nop 1
	v_mov_b32_dpp v17, v53 row_shr:4 row_mask:0xf bank_mask:0xa
	v_mov_b32_dpp v17, v53 row_shl:4 row_mask:0xf bank_mask:0x5
	v_mul_f32_e32 v205, v23, v47
	v_cndmask_b32_e64 v44, v52, v52, s[40:41]
	v_cndmask_b32_e64 v44, v44, v44, s[40:41]
	v_cndmask_b32_e64 v44, v44, v44, s[40:41]
	s_waitcnt lgkmcnt(0)
	v_mul_f32_e32 v17, v50, v17
	v_cndmask_b32_e64 v17, v17, -v17, s[36:37]
	v_fmac_f32_e32 v17, v49, v53
	v_cndmask_b32_e64 v17, v17, v53, s[40:41]
	v_pk_mov_b32 v[46:47], v[16:17], v[2:3] op_sel:[1,0]
	s_nop 0
	v_pk_mul_f32 v[46:47], v[46:47], v[204:205]
	s_nop 1
	v_mov_b32_dpp v52, v47 row_shr:4 row_mask:0xf bank_mask:0xa
	v_mov_b32_dpp v52, v47 row_shl:4 row_mask:0xf bank_mask:0x5
	v_mov_b32_e32 v17, v46
	v_cndmask_b32_e64 v17, v17, v46, s[40:41]
	v_mul_f32_e32 v205, v23, v45
	v_cndmask_b32_e64 v17, v17, v17, s[40:41]
	s_waitcnt lgkmcnt(0)
	v_mul_f32_e32 v52, v48, v52
	v_cndmask_b32_e64 v52, v52, -v52, s[36:37]
	v_fmac_f32_e32 v52, v25, v47
	v_cndmask_b32_e64 v46, v52, v47, s[40:41]
	v_mov_b32_e32 v47, v3
	v_pk_mul_f32 v[46:47], v[46:47], v[204:205]
	s_nop 1
	v_mov_b32_dpp v23, v47 row_shr:4 row_mask:0xf bank_mask:0xa
	v_mov_b32_dpp v23, v47 row_shl:4 row_mask:0xf bank_mask:0x5
	v_cndmask_b32_e64 v45, v46, v46, s[40:41]
	v_cvt_pk_bf16_f32 v44, v44, v17
	v_mov_b32_e32 v17, v161
	s_waitcnt lgkmcnt(0)
	v_mul_f32_e32 v23, v21, v23
	v_cndmask_b32_e64 v23, v23, -v23, s[36:37]
	v_fmac_f32_e32 v23, v9, v47
	v_cndmask_b32_e64 v23, v23, v47, s[40:41]
	v_mul_f32_e32 v23, 0x3e38aa3b, v23
	v_cvt_pk_bf16_f32 v45, v45, v23
	v_lshl_add_u64 v[46:47], v[34:35], 0, v[16:17]
	global_store_dwordx2 v[46:47], v[44:45], off offset:512
	v_lshlrev_b32_e32 v45, 16, v39
	v_lshlrev_b32_e32 v44, 16, v38
	v_and_b32_e32 v39, 0xffff0000, v39
	v_and_b32_e32 v38, 0xffff0000, v38
	v_pk_mul_f32 v[46:47], v[38:39], v[38:39]
	s_nop 0
	v_pk_fma_f32 v[46:47], v[44:45], v[44:45], v[46:47]
	s_nop 0
	v_add_f32_e32 v17, v46, v47
	s_nop 1
	v_add_f32_dpp v17, v17, v17 quad_perm:[1,0,3,2] row_mask:0xf bank_mask:0xf bound_ctrl:1
	s_nop 1
	v_add_f32_dpp v17, v17, v17 quad_perm:[2,3,0,1] row_mask:0xf bank_mask:0xf bound_ctrl:1
	s_nop 1
	v_add_f32_dpp v17, v17, v17 row_ror:4 row_mask:0xf bank_mask:0xf bound_ctrl:1
	s_nop 1
	v_add_f32_dpp v17, v17, v17 row_ror:8 row_mask:0xf bank_mask:0xf bound_ctrl:1
	v_fmamk_f32 v17, v17, 0x3c800000, v237
	v_rsq_f32_e32 v46, v17
	s_nop 0
	v_mul_f32_e32 v17, v46, v44
	v_mul_f32_e32 v17, v4, v17
	s_nop 1
	v_mov_b32_dpp v23, v17 row_shr:4 row_mask:0xf bank_mask:0xa
	v_mov_b32_dpp v23, v17 row_shl:4 row_mask:0xf bank_mask:0x5
	s_waitcnt lgkmcnt(0)
	v_mul_f32_e32 v23, v56, v23
	v_cndmask_b32_e64 v23, v23, -v23, s[36:37]
	v_fmac_f32_e32 v23, v51, v17
	v_cndmask_b32_e64 v17, v23, v17, s[40:41]
	v_mul_f32_e32 v23, v46, v38
	v_mul_f32_e32 v23, v5, v23
	s_nop 1
	v_mov_b32_dpp v38, v23 row_shr:4 row_mask:0xf bank_mask:0xa
	v_mov_b32_dpp v38, v23 row_shl:4 row_mask:0xf bank_mask:0x5
	s_waitcnt lgkmcnt(0)
	v_mul_f32_e32 v38, v50, v38
	v_cndmask_b32_e64 v38, v38, -v38, s[36:37]
	v_fmac_f32_e32 v38, v49, v23
	v_cndmask_b32_e64 v23, v38, v23, s[40:41]
	v_mul_f32_e32 v38, v46, v45
	v_mul_f32_e32 v38, v6, v38
	s_nop 1
	v_mov_b32_dpp v44, v38 row_shr:4 row_mask:0xf bank_mask:0xa
	v_mov_b32_dpp v44, v38 row_shl:4 row_mask:0xf bank_mask:0x5
	s_waitcnt lgkmcnt(0)
	v_mul_f32_e32 v44, v48, v44
	v_cndmask_b32_e64 v44, v44, -v44, s[36:37]
	v_fmac_f32_e32 v44, v25, v38
	v_cndmask_b32_e64 v25, v44, v38, s[40:41]
	v_mul_f32_e32 v38, v46, v39
	v_mul_f32_e32 v38, v7, v38
	s_nop 1
	v_mov_b32_dpp v39, v38 row_shr:4 row_mask:0xf bank_mask:0xa
	v_mov_b32_dpp v39, v38 row_shl:4 row_mask:0xf bank_mask:0x5
	s_waitcnt lgkmcnt(0)
	v_mul_f32_e32 v21, v21, v39
	v_cndmask_b32_e64 v21, v21, -v21, s[36:37]
	v_fmac_f32_e32 v21, v9, v38
	v_cndmask_b32_e64 v9, v21, v38, s[40:41]
	s_and_saveexec_b64 s[0:1], vcc
	s_cbranch_execz .LBB0_452
	v_cvt_pk_bf16_f32 v39, v25, v9
	v_mov_b32_e32 v25, v161
	v_cvt_pk_bf16_f32 v38, v17, v23
	v_lshl_add_u64 v[34:35], v[34:35], 0, v[24:25]
	global_store_dwordx2 v[34:35], v[38:39], off offset:512
	s_branch .LBB0_452

.LBB0_498:
	s_or_b64 exec, exec, s[2:3]
	v_lshrrev_b32_e32 v9, 6, v9
	v_and_b32_e32 v17, 63, v26
	v_cndmask_b32_e64 v9, v17, v9, s[38:39]
	v_cvt_f32_ubyte0_e32 v9, v9
	v_mul_f32_e32 v17, v59, v9
	v_mul_f32_e32 v17, 0.15915494, v17
	v_cos_f32_e32 v51, v17
	v_sin_f32_e32 v56, v17
	v_mul_f32_e32 v17, v60, v9
	v_mul_f32_e32 v17, 0.15915494, v17
	v_cos_f32_e32 v49, v17
	v_sin_f32_e32 v50, v17
	v_mul_f32_e32 v17, v61, v9
	v_lshlrev_b32_e32 v53, 16, v47
	v_lshlrev_b32_e32 v52, 16, v46
	v_and_b32_e32 v47, 0xffff0000, v47
	v_and_b32_e32 v46, 0xffff0000, v46
	v_mul_f32_e32 v17, 0.15915494, v17
	v_mul_f32_e32 v9, v62, v9
	v_pk_mul_f32 v[54:55], v[46:47], v[46:47]
	v_cos_f32_e32 v25, v17
	v_sin_f32_e32 v48, v17
	v_mul_f32_e32 v17, 0.15915494, v9
	v_pk_fma_f32 v[54:55], v[52:53], v[52:53], v[54:55]
	v_cos_f32_e32 v9, v17
	v_sin_f32_e32 v21, v17
	v_add_f32_e32 v17, v54, v55
	v_mov_b32_e32 v55, v1
	s_nop 0
	v_add_f32_dpp v17, v17, v17 quad_perm:[1,0,3,2] row_mask:0xf bank_mask:0xf bound_ctrl:1
	s_nop 1
	v_add_f32_dpp v17, v17, v17 quad_perm:[2,3,0,1] row_mask:0xf bank_mask:0xf bound_ctrl:1
	s_nop 1
	v_add_f32_dpp v17, v17, v17 row_ror:4 row_mask:0xf bank_mask:0xf bound_ctrl:1
	s_nop 1
	v_add_f32_dpp v17, v17, v17 row_ror:8 row_mask:0xf bank_mask:0xf bound_ctrl:1
	v_fmamk_f32 v17, v17, 0x3c800000, v237
	v_rsq_f32_e32 v23, v17
	s_nop 0
	v_mul_f32_e32 v17, v23, v52
	v_mul_f32_e32 v17, v0, v17
	s_nop 1
	v_mov_b32_dpp v52, v17 row_shr:4 row_mask:0xf bank_mask:0xa
	v_mov_b32_dpp v52, v17 row_shl:4 row_mask:0xf bank_mask:0x5
	v_mul_f32_e32 v205, v23, v46
	s_waitcnt lgkmcnt(0)
	v_mul_f32_e32 v52, v56, v52
	v_cndmask_b32_e64 v52, v52, -v52, s[36:37]
	v_fmac_f32_e32 v52, v51, v17
	v_cndmask_b32_e64 v54, v52, v17, s[40:41]
	v_pk_mul_f32 v[54:55], v[54:55], v[204:205]
	s_nop 1
	v_mov_b32_dpp v17, v55 row_shr:4 row_mask:0xf bank_mask:0xa
	v_mov_b32_dpp v17, v55 row_shl:4 row_mask:0xf bank_mask:0x5
	v_mul_f32_e32 v205, v23, v53
	v_cndmask_b32_e64 v46, v54, v54, s[40:41]
	v_cndmask_b32_e64 v46, v46, v46, s[40:41]
	v_cndmask_b32_e64 v46, v46, v46, s[40:41]
	s_waitcnt lgkmcnt(0)
	v_mul_f32_e32 v17, v50, v17
	v_cndmask_b32_e64 v17, v17, -v17, s[36:37]
	v_fmac_f32_e32 v17, v49, v55
	v_cndmask_b32_e64 v17, v17, v55, s[40:41]
	v_pk_mov_b32 v[52:53], v[16:17], v[2:3] op_sel:[1,0]
	s_nop 0
	v_pk_mul_f32 v[52:53], v[52:53], v[204:205]
	s_nop 1
	v_mov_b32_dpp v54, v53 row_shr:4 row_mask:0xf bank_mask:0xa
	v_mov_b32_dpp v54, v53 row_shl:4 row_mask:0xf bank_mask:0x5
	v_mov_b32_e32 v17, v52
	v_cndmask_b32_e64 v17, v17, v52, s[40:41]
	v_mul_f32_e32 v205, v23, v47
	s_waitcnt lgkmcnt(0)
	v_mul_f32_e32 v54, v48, v54
	v_cndmask_b32_e64 v54, v54, -v54, s[36:37]
	v_fmac_f32_e32 v54, v25, v53
	v_cndmask_b32_e64 v52, v54, v53, s[40:41]
	v_mov_b32_e32 v53, v3
	v_pk_mul_f32 v[52:53], v[52:53], v[204:205]
	s_nop 1
	v_mov_b32_dpp v23, v53 row_shr:4 row_mask:0xf bank_mask:0xa
	v_mov_b32_dpp v23, v53 row_shl:4 row_mask:0xf bank_mask:0x5
	v_cndmask_b32_e64 v47, v52, v52, s[40:41]
	v_cndmask_b32_e64 v52, v17, v17, s[40:41]
	v_cvt_pk_bf16_f32 v46, v46, v52
	s_waitcnt lgkmcnt(0)
	v_mul_f32_e32 v23, v21, v23
	v_cndmask_b32_e64 v23, v23, -v23, s[36:37]
	v_fmac_f32_e32 v23, v9, v53
	v_cndmask_b32_e64 v17, v23, v53, s[40:41]
	v_mul_f32_e32 v17, 0x3e38aa3b, v17
	v_mov_b32_e32 v23, v161
	v_cvt_pk_bf16_f32 v47, v47, v17
	v_lshl_add_u64 v[52:53], v[34:35], 0, v[22:23]
	global_store_dwordx2 v[52:53], v[46:47], off offset:512
	v_lshlrev_b32_e32 v47, 16, v45
	v_lshlrev_b32_e32 v46, 16, v44
	v_and_b32_e32 v45, 0xffff0000, v45
	v_and_b32_e32 v44, 0xffff0000, v44
	v_pk_mul_f32 v[52:53], v[44:45], v[44:45]
	s_nop 0
	v_pk_fma_f32 v[52:53], v[46:47], v[46:47], v[52:53]
	s_nop 0
	v_add_f32_e32 v17, v52, v53
	v_mov_b32_e32 v53, v1
	s_nop 0
	v_add_f32_dpp v17, v17, v17 quad_perm:[1,0,3,2] row_mask:0xf bank_mask:0xf bound_ctrl:1
	s_nop 1
	v_add_f32_dpp v17, v17, v17 quad_perm:[2,3,0,1] row_mask:0xf bank_mask:0xf bound_ctrl:1
	s_nop 1
	v_add_f32_dpp v17, v17, v17 row_ror:4 row_mask:0xf bank_mask:0xf bound_ctrl:1
	s_nop 1
	v_add_f32_dpp v17, v17, v17 row_ror:8 row_mask:0xf bank_mask:0xf bound_ctrl:1
	v_fmamk_f32 v17, v17, 0x3c800000, v237
	v_rsq_f32_e32 v23, v17
	s_nop 0
	v_mul_f32_e32 v17, v23, v46
	v_mul_f32_e32 v17, v0, v17
	s_nop 1
	v_mov_b32_dpp v46, v17 row_shr:4 row_mask:0xf bank_mask:0xa
	v_mov_b32_dpp v46, v17 row_shl:4 row_mask:0xf bank_mask:0x5
	v_mul_f32_e32 v205, v23, v44
	s_waitcnt lgkmcnt(0)
	v_mul_f32_e32 v46, v56, v46
	v_cndmask_b32_e64 v46, v46, -v46, s[36:37]
	v_fmac_f32_e32 v46, v51, v17
	v_cndmask_b32_e64 v52, v46, v17, s[40:41]
	v_pk_mul_f32 v[52:53], v[52:53], v[204:205]
	s_nop 1
	v_mov_b32_dpp v17, v53 row_shr:4 row_mask:0xf bank_mask:0xa
	v_mov_b32_dpp v17, v53 row_shl:4 row_mask:0xf bank_mask:0x5
	v_mul_f32_e32 v205, v23, v47
	v_cndmask_b32_e64 v44, v52, v52, s[40:41]
	v_cndmask_b32_e64 v44, v44, v44, s[40:41]
	v_cndmask_b32_e64 v44, v44, v44, s[40:41]
	s_waitcnt lgkmcnt(0)
	v_mul_f32_e32 v17, v50, v17
	v_cndmask_b32_e64 v17, v17, -v17, s[36:37]
	v_fmac_f32_e32 v17, v49, v53
	v_cndmask_b32_e64 v17, v17, v53, s[40:41]
	v_pk_mov_b32 v[46:47], v[16:17], v[2:3] op_sel:[1,0]
	s_nop 0
	v_pk_mul_f32 v[46:47], v[46:47], v[204:205]
	s_nop 1
	v_mov_b32_dpp v52, v47 row_shr:4 row_mask:0xf bank_mask:0xa
	v_mov_b32_dpp v52, v47 row_shl:4 row_mask:0xf bank_mask:0x5
	v_mov_b32_e32 v17, v46
	v_cndmask_b32_e64 v17, v17, v46, s[40:41]
	v_mul_f32_e32 v205, v23, v45
	v_cndmask_b32_e64 v17, v17, v17, s[40:41]
	s_waitcnt lgkmcnt(0)
	v_mul_f32_e32 v52, v48, v52
	v_cndmask_b32_e64 v52, v52, -v52, s[36:37]
	v_fmac_f32_e32 v52, v25, v47
	v_cndmask_b32_e64 v46, v52, v47, s[40:41]
	v_mov_b32_e32 v47, v3
	v_pk_mul_f32 v[46:47], v[46:47], v[204:205]
	s_nop 1
	v_mov_b32_dpp v23, v47 row_shr:4 row_mask:0xf bank_mask:0xa
	v_mov_b32_dpp v23, v47 row_shl:4 row_mask:0xf bank_mask:0x5
	v_cndmask_b32_e64 v45, v46, v46, s[40:41]
	v_cvt_pk_bf16_f32 v44, v44, v17
	v_mov_b32_e32 v17, v161
	s_waitcnt lgkmcnt(0)
	v_mul_f32_e32 v23, v21, v23
	v_cndmask_b32_e64 v23, v23, -v23, s[36:37]
	v_fmac_f32_e32 v23, v9, v47
	v_cndmask_b32_e64 v23, v23, v47, s[40:41]
	v_mul_f32_e32 v23, 0x3e38aa3b, v23
	v_cvt_pk_bf16_f32 v45, v45, v23
	v_lshl_add_u64 v[46:47], v[34:35], 0, v[16:17]
	global_store_dwordx2 v[46:47], v[44:45], off offset:512
	v_lshlrev_b32_e32 v45, 16, v39
	v_lshlrev_b32_e32 v44, 16, v38
	v_and_b32_e32 v39, 0xffff0000, v39
	v_and_b32_e32 v38, 0xffff0000, v38
	v_pk_mul_f32 v[46:47], v[38:39], v[38:39]
	s_nop 0
	v_pk_fma_f32 v[46:47], v[44:45], v[44:45], v[46:47]
	s_nop 0
	v_add_f32_e32 v17, v46, v47
	s_nop 1
	v_add_f32_dpp v17, v17, v17 quad_perm:[1,0,3,2] row_mask:0xf bank_mask:0xf bound_ctrl:1
	s_nop 1
	v_add_f32_dpp v17, v17, v17 quad_perm:[2,3,0,1] row_mask:0xf bank_mask:0xf bound_ctrl:1
	s_nop 1
	v_add_f32_dpp v17, v17, v17 row_ror:4 row_mask:0xf bank_mask:0xf bound_ctrl:1
	s_nop 1
	v_add_f32_dpp v17, v17, v17 row_ror:8 row_mask:0xf bank_mask:0xf bound_ctrl:1
	v_fmamk_f32 v17, v17, 0x3c800000, v237
	v_rsq_f32_e32 v46, v17
	s_nop 0
	v_mul_f32_e32 v17, v46, v44
	v_mul_f32_e32 v17, v4, v17
	s_nop 1
	v_mov_b32_dpp v23, v17 row_shr:4 row_mask:0xf bank_mask:0xa
	v_mov_b32_dpp v23, v17 row_shl:4 row_mask:0xf bank_mask:0x5
	s_waitcnt lgkmcnt(0)
	v_mul_f32_e32 v23, v56, v23
	v_cndmask_b32_e64 v23, v23, -v23, s[36:37]
	v_fmac_f32_e32 v23, v51, v17
	v_cndmask_b32_e64 v17, v23, v17, s[40:41]
	v_mul_f32_e32 v23, v46, v38
	v_mul_f32_e32 v23, v5, v23
	s_nop 1
	v_mov_b32_dpp v38, v23 row_shr:4 row_mask:0xf bank_mask:0xa
	v_mov_b32_dpp v38, v23 row_shl:4 row_mask:0xf bank_mask:0x5
	s_waitcnt lgkmcnt(0)
	v_mul_f32_e32 v38, v50, v38
	v_cndmask_b32_e64 v38, v38, -v38, s[36:37]
	v_fmac_f32_e32 v38, v49, v23
	v_cndmask_b32_e64 v23, v38, v23, s[40:41]
	v_mul_f32_e32 v38, v46, v45
	v_mul_f32_e32 v38, v6, v38
	s_nop 1
	v_mov_b32_dpp v44, v38 row_shr:4 row_mask:0xf bank_mask:0xa
	v_mov_b32_dpp v44, v38 row_shl:4 row_mask:0xf bank_mask:0x5
	s_waitcnt lgkmcnt(0)
	v_mul_f32_e32 v44, v48, v44
	v_cndmask_b32_e64 v44, v44, -v44, s[36:37]
	v_fmac_f32_e32 v44, v25, v38
	v_cndmask_b32_e64 v25, v44, v38, s[40:41]
	v_mul_f32_e32 v38, v46, v39
	v_mul_f32_e32 v38, v7, v38
	s_nop 1
	v_mov_b32_dpp v39, v38 row_shr:4 row_mask:0xf bank_mask:0xa
	v_mov_b32_dpp v39, v38 row_shl:4 row_mask:0xf bank_mask:0x5
	s_waitcnt lgkmcnt(0)
	v_mul_f32_e32 v21, v21, v39
	v_cndmask_b32_e64 v21, v21, -v21, s[36:37]
	v_fmac_f32_e32 v21, v9, v38
	v_cndmask_b32_e64 v9, v21, v38, s[40:41]
	s_and_saveexec_b64 s[0:1], vcc
	s_cbranch_execz .LBB0_477
	v_cvt_pk_bf16_f32 v39, v25, v9
	v_mov_b32_e32 v25, v161
	v_cvt_pk_bf16_f32 v38, v17, v23
	v_lshl_add_u64 v[34:35], v[34:35], 0, v[24:25]
	global_store_dwordx2 v[34:35], v[38:39], off offset:512
	s_branch .LBB0_477

.LBB0_528:
	s_or_b64 exec, exec, s[4:5]
	v_lshrrev_b32_e32 v9, 6, v9
	v_and_b32_e32 v19, 63, v160
	v_cndmask_b32_e64 v9, v19, v9, s[38:39]
	v_cvt_f32_ubyte0_e32 v9, v9
	v_mul_f32_e32 v19, v56, v9
	v_mul_f32_e32 v19, 0.15915494, v19
	v_cos_f32_e32 v48, v19
	v_sin_f32_e32 v49, v19
	v_mul_f32_e32 v19, v57, v9
	v_mul_f32_e32 v19, 0.15915494, v19
	v_lshlrev_b32_e32 v51, 16, v43
	v_lshlrev_b32_e32 v50, 16, v42
	v_and_b32_e32 v43, 0xffff0000, v43
	v_and_b32_e32 v42, 0xffff0000, v42
	v_cos_f32_e32 v46, v19
	v_sin_f32_e32 v47, v19
	v_mul_f32_e32 v19, v58, v9
	v_mul_f32_e32 v9, v59, v9
	v_pk_mul_f32 v[52:53], v[42:43], v[42:43]
	v_mul_f32_e32 v19, 0.15915494, v19
	v_mul_f32_e32 v9, 0.15915494, v9
	v_pk_fma_f32 v[52:53], v[50:51], v[50:51], v[52:53]
	v_cos_f32_e32 v44, v19
	v_sin_f32_e32 v45, v19
	v_cos_f32_e32 v19, v9
	v_sin_f32_e32 v23, v9
	v_add_f32_e32 v9, v52, v53
	v_mov_b32_e32 v53, v1
	s_nop 0
	v_add_f32_dpp v9, v9, v9 quad_perm:[1,0,3,2] row_mask:0xf bank_mask:0xf bound_ctrl:1
	s_nop 1
	v_add_f32_dpp v9, v9, v9 quad_perm:[2,3,0,1] row_mask:0xf bank_mask:0xf bound_ctrl:1
	s_nop 1
	v_add_f32_dpp v9, v9, v9 row_ror:4 row_mask:0xf bank_mask:0xf bound_ctrl:1
	s_nop 1
	v_add_f32_dpp v9, v9, v9 row_ror:8 row_mask:0xf bank_mask:0xf bound_ctrl:1
	v_fmamk_f32 v9, v9, 0x3c800000, v237
	v_rsq_f32_e32 v21, v9
	s_nop 0
	v_mul_f32_e32 v9, v21, v50
	v_mul_f32_e32 v9, v0, v9
	s_nop 1
	v_mov_b32_dpp v50, v9 row_shr:4 row_mask:0xf bank_mask:0xa
	v_mov_b32_dpp v50, v9 row_shl:4 row_mask:0xf bank_mask:0x5
	v_mul_f32_e32 v205, v21, v42
	s_waitcnt lgkmcnt(0)
	v_mul_f32_e32 v50, v49, v50
	v_cndmask_b32_e64 v50, v50, -v50, s[36:37]
	v_fmac_f32_e32 v50, v48, v9
	v_cndmask_b32_e64 v52, v50, v9, s[40:41]
	v_pk_mul_f32 v[52:53], v[52:53], v[204:205]
	s_nop 1
	v_mov_b32_dpp v9, v53 row_shr:4 row_mask:0xf bank_mask:0xa
	v_mov_b32_dpp v9, v53 row_shl:4 row_mask:0xf bank_mask:0x5
	v_mul_f32_e32 v205, v21, v51
	v_cndmask_b32_e64 v42, v52, v52, s[40:41]
	v_cndmask_b32_e64 v42, v42, v42, s[40:41]
	v_cndmask_b32_e64 v42, v42, v42, s[40:41]
	s_waitcnt lgkmcnt(0)
	v_mul_f32_e32 v9, v47, v9
	v_cndmask_b32_e64 v9, v9, -v9, s[36:37]
	v_fmac_f32_e32 v9, v46, v53
	v_cndmask_b32_e64 v9, v9, v53, s[40:41]
	v_pk_mov_b32 v[50:51], v[8:9], v[2:3] op_sel:[1,0]
	s_nop 0
	v_pk_mul_f32 v[50:51], v[50:51], v[204:205]
	s_nop 1
	v_mov_b32_dpp v52, v51 row_shr:4 row_mask:0xf bank_mask:0xa
	v_mov_b32_dpp v52, v51 row_shl:4 row_mask:0xf bank_mask:0x5
	v_mov_b32_e32 v9, v50
	v_cndmask_b32_e64 v9, v9, v50, s[40:41]
	v_mul_f32_e32 v205, v21, v43
	s_waitcnt lgkmcnt(0)
	v_mul_f32_e32 v52, v45, v52
	v_cndmask_b32_e64 v52, v52, -v52, s[36:37]
	v_fmac_f32_e32 v52, v44, v51
	v_cndmask_b32_e64 v50, v52, v51, s[40:41]
	v_mov_b32_e32 v51, v3
	v_pk_mul_f32 v[50:51], v[50:51], v[204:205]
	s_nop 1
	v_mov_b32_dpp v21, v51 row_shr:4 row_mask:0xf bank_mask:0xa
	v_mov_b32_dpp v21, v51 row_shl:4 row_mask:0xf bank_mask:0x5
	v_cndmask_b32_e64 v43, v50, v50, s[40:41]
	v_cndmask_b32_e64 v50, v9, v9, s[40:41]
	v_cvt_pk_bf16_f32 v42, v42, v50
	s_waitcnt lgkmcnt(0)
	v_mul_f32_e32 v21, v23, v21
	v_cndmask_b32_e64 v21, v21, -v21, s[36:37]
	v_fmac_f32_e32 v21, v19, v51
	v_cndmask_b32_e64 v9, v21, v51, s[40:41]
	v_mul_f32_e32 v9, 0x3e38aa3b, v9
	v_mov_b32_e32 v21, v161
	v_cvt_pk_bf16_f32 v43, v43, v9
	v_lshl_add_u64 v[50:51], v[30:31], 0, v[20:21]
	global_store_dwordx2 v[50:51], v[42:43], off offset:512
	v_lshlrev_b32_e32 v43, 16, v41
	v_lshlrev_b32_e32 v42, 16, v40
	v_and_b32_e32 v41, 0xffff0000, v41
	v_and_b32_e32 v40, 0xffff0000, v40
	v_pk_mul_f32 v[50:51], v[40:41], v[40:41]
	s_nop 0
	v_pk_fma_f32 v[50:51], v[42:43], v[42:43], v[50:51]
	s_nop 0
	v_add_f32_e32 v9, v50, v51
	v_mov_b32_e32 v51, v1
	s_nop 0
	v_add_f32_dpp v9, v9, v9 quad_perm:[1,0,3,2] row_mask:0xf bank_mask:0xf bound_ctrl:1
	s_nop 1
	v_add_f32_dpp v9, v9, v9 quad_perm:[2,3,0,1] row_mask:0xf bank_mask:0xf bound_ctrl:1
	s_nop 1
	v_add_f32_dpp v9, v9, v9 row_ror:4 row_mask:0xf bank_mask:0xf bound_ctrl:1
	s_nop 1
	v_add_f32_dpp v9, v9, v9 row_ror:8 row_mask:0xf bank_mask:0xf bound_ctrl:1
	v_fmamk_f32 v9, v9, 0x3c800000, v237
	v_rsq_f32_e32 v21, v9
	s_nop 0
	v_mul_f32_e32 v9, v21, v42
	v_mul_f32_e32 v9, v0, v9
	s_nop 1
	v_mov_b32_dpp v42, v9 row_shr:4 row_mask:0xf bank_mask:0xa
	v_mov_b32_dpp v42, v9 row_shl:4 row_mask:0xf bank_mask:0x5
	v_mul_f32_e32 v205, v21, v40
	s_waitcnt lgkmcnt(0)
	v_mul_f32_e32 v42, v49, v42
	v_cndmask_b32_e64 v42, v42, -v42, s[36:37]
	v_fmac_f32_e32 v42, v48, v9
	v_cndmask_b32_e64 v50, v42, v9, s[40:41]
	v_pk_mul_f32 v[50:51], v[50:51], v[204:205]
	s_nop 1
	v_mov_b32_dpp v9, v51 row_shr:4 row_mask:0xf bank_mask:0xa
	v_mov_b32_dpp v9, v51 row_shl:4 row_mask:0xf bank_mask:0x5
	v_mul_f32_e32 v205, v21, v43
	v_cndmask_b32_e64 v40, v50, v50, s[40:41]
	v_cndmask_b32_e64 v40, v40, v40, s[40:41]
	v_cndmask_b32_e64 v40, v40, v40, s[40:41]
	s_waitcnt lgkmcnt(0)
	v_mul_f32_e32 v9, v47, v9
	v_cndmask_b32_e64 v9, v9, -v9, s[36:37]
	v_fmac_f32_e32 v9, v46, v51
	v_cndmask_b32_e64 v9, v9, v51, s[40:41]
	v_pk_mov_b32 v[42:43], v[8:9], v[2:3] op_sel:[1,0]
	s_nop 0
	v_pk_mul_f32 v[42:43], v[42:43], v[204:205]
	s_nop 1
	v_mov_b32_dpp v50, v43 row_shr:4 row_mask:0xf bank_mask:0xa
	v_mov_b32_dpp v50, v43 row_shl:4 row_mask:0xf bank_mask:0x5
	v_mov_b32_e32 v9, v42
	v_cndmask_b32_e64 v9, v9, v42, s[40:41]
	v_mul_f32_e32 v205, v21, v41
	v_cndmask_b32_e64 v9, v9, v9, s[40:41]
	s_waitcnt lgkmcnt(0)
	v_mul_f32_e32 v50, v45, v50
	v_cndmask_b32_e64 v50, v50, -v50, s[36:37]
	v_fmac_f32_e32 v50, v44, v43
	v_cndmask_b32_e64 v42, v50, v43, s[40:41]
	v_mov_b32_e32 v43, v3
	v_pk_mul_f32 v[42:43], v[42:43], v[204:205]
	s_nop 1
	v_mov_b32_dpp v21, v43 row_shr:4 row_mask:0xf bank_mask:0xa
	v_mov_b32_dpp v21, v43 row_shl:4 row_mask:0xf bank_mask:0x5
	v_cndmask_b32_e64 v41, v42, v42, s[40:41]
	v_cvt_pk_bf16_f32 v40, v40, v9
	v_mov_b32_e32 v9, v161
	s_waitcnt lgkmcnt(0)
	v_mul_f32_e32 v21, v23, v21
	v_cndmask_b32_e64 v21, v21, -v21, s[36:37]
	v_fmac_f32_e32 v21, v19, v43
	v_cndmask_b32_e64 v21, v21, v43, s[40:41]
	v_mul_f32_e32 v21, 0x3e38aa3b, v21
	v_cvt_pk_bf16_f32 v41, v41, v21
	v_lshl_add_u64 v[42:43], v[30:31], 0, v[8:9]
	global_store_dwordx2 v[42:43], v[40:41], off offset:512
	v_and_b32_e32 v43, 0xffff0000, v35
	v_and_b32_e32 v42, 0xffff0000, v34
	v_lshlrev_b32_e32 v41, 16, v35
	v_lshlrev_b32_e32 v40, 16, v34
	v_pk_mul_f32 v[34:35], v[42:43], v[42:43]
	s_nop 0
	v_pk_fma_f32 v[34:35], v[40:41], v[40:41], v[34:35]
	s_nop 0
	v_add_f32_e32 v9, v34, v35
	s_nop 1
	v_add_f32_dpp v9, v9, v9 quad_perm:[1,0,3,2] row_mask:0xf bank_mask:0xf bound_ctrl:1
	s_nop 1
	v_add_f32_dpp v9, v9, v9 quad_perm:[2,3,0,1] row_mask:0xf bank_mask:0xf bound_ctrl:1
	s_nop 1
	v_add_f32_dpp v9, v9, v9 row_ror:4 row_mask:0xf bank_mask:0xf bound_ctrl:1
	s_nop 1
	v_add_f32_dpp v9, v9, v9 row_ror:8 row_mask:0xf bank_mask:0xf bound_ctrl:1
	v_fmamk_f32 v9, v9, 0x3c800000, v237
	v_rsq_f32_e32 v9, v9
	s_nop 0
	v_mul_f32_e32 v21, v9, v40
	v_mul_f32_e32 v21, v4, v21
	s_nop 1
	v_mov_b32_dpp v34, v21 row_shr:4 row_mask:0xf bank_mask:0xa
	v_mov_b32_dpp v34, v21 row_shl:4 row_mask:0xf bank_mask:0x5
	s_waitcnt lgkmcnt(0)
	v_mul_f32_e32 v34, v49, v34
	v_cndmask_b32_e64 v34, v34, -v34, s[36:37]
	v_fmac_f32_e32 v34, v48, v21
	v_cndmask_b32_e64 v21, v34, v21, s[40:41]
	v_mul_f32_e32 v34, v9, v42
	v_mul_f32_e32 v34, v5, v34
	s_nop 1
	v_mov_b32_dpp v35, v34 row_shr:4 row_mask:0xf bank_mask:0xa
	v_mov_b32_dpp v35, v34 row_shl:4 row_mask:0xf bank_mask:0x5
	s_waitcnt lgkmcnt(0)
	v_mul_f32_e32 v35, v47, v35
	v_cndmask_b32_e64 v35, v35, -v35, s[36:37]
	v_fmac_f32_e32 v35, v46, v34
	v_cndmask_b32_e64 v34, v35, v34, s[40:41]
	v_mul_f32_e32 v35, v9, v41
	v_mul_f32_e32 v35, v6, v35
	s_nop 1
	v_mov_b32_dpp v40, v35 row_shr:4 row_mask:0xf bank_mask:0xa
	v_mov_b32_dpp v40, v35 row_shl:4 row_mask:0xf bank_mask:0x5
	v_mul_f32_e32 v9, v9, v43
	v_mul_f32_e32 v9, v7, v9
	s_waitcnt lgkmcnt(0)
	v_mul_f32_e32 v40, v45, v40
	v_cndmask_b32_e64 v40, v40, -v40, s[36:37]
	v_fmac_f32_e32 v40, v44, v35
	v_cndmask_b32_e64 v35, v40, v35, s[40:41]
	s_nop 1
	v_mov_b32_dpp v40, v9 row_shr:4 row_mask:0xf bank_mask:0xa
	v_mov_b32_dpp v40, v9 row_shl:4 row_mask:0xf bank_mask:0x5
	s_waitcnt lgkmcnt(0)
	v_mul_f32_e32 v23, v23, v40
	v_cndmask_b32_e64 v23, v23, -v23, s[36:37]
	v_fmac_f32_e32 v23, v19, v9
	v_cndmask_b32_e64 v9, v23, v9, s[40:41]
	s_and_saveexec_b64 s[0:1], vcc
	s_cbranch_execz .LBB0_507
	v_mov_b32_e32 v23, v161
	v_cvt_pk_bf16_f32 v34, v21, v34
	v_cvt_pk_bf16_f32 v35, v35, v9
	v_lshl_add_u64 v[30:31], v[30:31], 0, v[22:23]
	global_store_dwordx2 v[30:31], v[34:35], off offset:512
	s_branch .LBB0_507

.LBB0_554:
	s_or_b64 exec, exec, s[4:5]
	v_lshrrev_b32_e32 v9, 6, v9
	v_and_b32_e32 v19, 63, v24
	v_cndmask_b32_e64 v9, v19, v9, s[38:39]
	v_cvt_f32_ubyte0_e32 v9, v9
	v_mul_f32_e32 v19, v58, v9
	v_mul_f32_e32 v19, 0.15915494, v19
	v_cos_f32_e32 v50, v19
	v_sin_f32_e32 v51, v19
	v_mul_f32_e32 v19, v59, v9
	v_mul_f32_e32 v19, 0.15915494, v19
	v_lshlrev_b32_e32 v53, 16, v45
	v_lshlrev_b32_e32 v52, 16, v44
	v_and_b32_e32 v45, 0xffff0000, v45
	v_and_b32_e32 v44, 0xffff0000, v44
	v_cos_f32_e32 v48, v19
	v_sin_f32_e32 v49, v19
	v_mul_f32_e32 v19, v60, v9
	v_mul_f32_e32 v9, v61, v9
	v_pk_mul_f32 v[54:55], v[44:45], v[44:45]
	v_mul_f32_e32 v19, 0.15915494, v19
	v_mul_f32_e32 v9, 0.15915494, v9
	v_pk_fma_f32 v[54:55], v[52:53], v[52:53], v[54:55]
	v_cos_f32_e32 v46, v19
	v_sin_f32_e32 v47, v19
	v_cos_f32_e32 v19, v9
	v_sin_f32_e32 v23, v9
	v_add_f32_e32 v9, v54, v55
	v_mov_b32_e32 v55, v1
	s_nop 0
	v_add_f32_dpp v9, v9, v9 quad_perm:[1,0,3,2] row_mask:0xf bank_mask:0xf bound_ctrl:1
	s_nop 1
	v_add_f32_dpp v9, v9, v9 quad_perm:[2,3,0,1] row_mask:0xf bank_mask:0xf bound_ctrl:1
	s_nop 1
	v_add_f32_dpp v9, v9, v9 row_ror:4 row_mask:0xf bank_mask:0xf bound_ctrl:1
	s_nop 1
	v_add_f32_dpp v9, v9, v9 row_ror:8 row_mask:0xf bank_mask:0xf bound_ctrl:1
	v_fmamk_f32 v9, v9, 0x3c800000, v237
	v_rsq_f32_e32 v21, v9
	s_nop 0
	v_mul_f32_e32 v9, v21, v52
	v_mul_f32_e32 v9, v0, v9
	s_nop 1
	v_mov_b32_dpp v52, v9 row_shr:4 row_mask:0xf bank_mask:0xa
	v_mov_b32_dpp v52, v9 row_shl:4 row_mask:0xf bank_mask:0x5
	v_mul_f32_e32 v205, v21, v44
	s_waitcnt lgkmcnt(0)
	v_mul_f32_e32 v52, v51, v52
	v_cndmask_b32_e64 v52, v52, -v52, s[36:37]
	v_fmac_f32_e32 v52, v50, v9
	v_cndmask_b32_e64 v54, v52, v9, s[40:41]
	v_pk_mul_f32 v[54:55], v[54:55], v[204:205]
	s_nop 1
	v_mov_b32_dpp v9, v55 row_shr:4 row_mask:0xf bank_mask:0xa
	v_mov_b32_dpp v9, v55 row_shl:4 row_mask:0xf bank_mask:0x5
	v_mul_f32_e32 v205, v21, v53
	v_cndmask_b32_e64 v44, v54, v54, s[40:41]
	v_cndmask_b32_e64 v44, v44, v44, s[40:41]
	v_cndmask_b32_e64 v44, v44, v44, s[40:41]
	s_waitcnt lgkmcnt(0)
	v_mul_f32_e32 v9, v49, v9
	v_cndmask_b32_e64 v9, v9, -v9, s[36:37]
	v_fmac_f32_e32 v9, v48, v55
	v_cndmask_b32_e64 v9, v9, v55, s[40:41]
	v_pk_mov_b32 v[52:53], v[8:9], v[2:3] op_sel:[1,0]
	s_nop 0
	v_pk_mul_f32 v[52:53], v[52:53], v[204:205]
	s_nop 1
	v_mov_b32_dpp v54, v53 row_shr:4 row_mask:0xf bank_mask:0xa
	v_mov_b32_dpp v54, v53 row_shl:4 row_mask:0xf bank_mask:0x5
	v_mov_b32_e32 v9, v52
	v_cndmask_b32_e64 v9, v9, v52, s[40:41]
	v_mul_f32_e32 v205, v21, v45
	s_waitcnt lgkmcnt(0)
	v_mul_f32_e32 v54, v47, v54
	v_cndmask_b32_e64 v54, v54, -v54, s[36:37]
	v_fmac_f32_e32 v54, v46, v53
	v_cndmask_b32_e64 v52, v54, v53, s[40:41]
	v_mov_b32_e32 v53, v3
	v_pk_mul_f32 v[52:53], v[52:53], v[204:205]
	s_nop 1
	v_mov_b32_dpp v21, v53 row_shr:4 row_mask:0xf bank_mask:0xa
	v_mov_b32_dpp v21, v53 row_shl:4 row_mask:0xf bank_mask:0x5
	v_cndmask_b32_e64 v45, v52, v52, s[40:41]
	v_cndmask_b32_e64 v52, v9, v9, s[40:41]
	v_cvt_pk_bf16_f32 v44, v44, v52
	s_waitcnt lgkmcnt(0)
	v_mul_f32_e32 v21, v23, v21
	v_cndmask_b32_e64 v21, v21, -v21, s[36:37]
	v_fmac_f32_e32 v21, v19, v53
	v_cndmask_b32_e64 v9, v21, v53, s[40:41]
	v_mul_f32_e32 v9, 0x3e38aa3b, v9
	v_mov_b32_e32 v21, v161
	v_cvt_pk_bf16_f32 v45, v45, v9
	v_lshl_add_u64 v[52:53], v[32:33], 0, v[20:21]
	global_store_dwordx2 v[52:53], v[44:45], off offset:512
	v_lshlrev_b32_e32 v45, 16, v43
	v_lshlrev_b32_e32 v44, 16, v42
	v_and_b32_e32 v43, 0xffff0000, v43
	v_and_b32_e32 v42, 0xffff0000, v42
	v_pk_mul_f32 v[52:53], v[42:43], v[42:43]
	s_nop 0
	v_pk_fma_f32 v[52:53], v[44:45], v[44:45], v[52:53]
	s_nop 0
	v_add_f32_e32 v9, v52, v53
	v_mov_b32_e32 v53, v1
	s_nop 0
	v_add_f32_dpp v9, v9, v9 quad_perm:[1,0,3,2] row_mask:0xf bank_mask:0xf bound_ctrl:1
	s_nop 1
	v_add_f32_dpp v9, v9, v9 quad_perm:[2,3,0,1] row_mask:0xf bank_mask:0xf bound_ctrl:1
	s_nop 1
	v_add_f32_dpp v9, v9, v9 row_ror:4 row_mask:0xf bank_mask:0xf bound_ctrl:1
	s_nop 1
	v_add_f32_dpp v9, v9, v9 row_ror:8 row_mask:0xf bank_mask:0xf bound_ctrl:1
	v_fmamk_f32 v9, v9, 0x3c800000, v237
	v_rsq_f32_e32 v21, v9
	s_nop 0
	v_mul_f32_e32 v9, v21, v44
	v_mul_f32_e32 v9, v0, v9
	s_nop 1
	v_mov_b32_dpp v44, v9 row_shr:4 row_mask:0xf bank_mask:0xa
	v_mov_b32_dpp v44, v9 row_shl:4 row_mask:0xf bank_mask:0x5
	v_mul_f32_e32 v205, v21, v42
	s_waitcnt lgkmcnt(0)
	v_mul_f32_e32 v44, v51, v44
	v_cndmask_b32_e64 v44, v44, -v44, s[36:37]
	v_fmac_f32_e32 v44, v50, v9
	v_cndmask_b32_e64 v52, v44, v9, s[40:41]
	v_pk_mul_f32 v[52:53], v[52:53], v[204:205]
	s_nop 1
	v_mov_b32_dpp v9, v53 row_shr:4 row_mask:0xf bank_mask:0xa
	v_mov_b32_dpp v9, v53 row_shl:4 row_mask:0xf bank_mask:0x5
	v_mul_f32_e32 v205, v21, v45
	v_cndmask_b32_e64 v42, v52, v52, s[40:41]
	v_cndmask_b32_e64 v42, v42, v42, s[40:41]
	v_cndmask_b32_e64 v42, v42, v42, s[40:41]
	s_waitcnt lgkmcnt(0)
	v_mul_f32_e32 v9, v49, v9
	v_cndmask_b32_e64 v9, v9, -v9, s[36:37]
	v_fmac_f32_e32 v9, v48, v53
	v_cndmask_b32_e64 v9, v9, v53, s[40:41]
	v_pk_mov_b32 v[44:45], v[8:9], v[2:3] op_sel:[1,0]
	s_nop 0
	v_pk_mul_f32 v[44:45], v[44:45], v[204:205]
	s_nop 1
	v_mov_b32_dpp v52, v45 row_shr:4 row_mask:0xf bank_mask:0xa
	v_mov_b32_dpp v52, v45 row_shl:4 row_mask:0xf bank_mask:0x5
	v_mov_b32_e32 v9, v44
	v_cndmask_b32_e64 v9, v9, v44, s[40:41]
	v_mul_f32_e32 v205, v21, v43
	v_cndmask_b32_e64 v9, v9, v9, s[40:41]
	s_waitcnt lgkmcnt(0)
	v_mul_f32_e32 v52, v47, v52
	v_cndmask_b32_e64 v52, v52, -v52, s[36:37]
	v_fmac_f32_e32 v52, v46, v45
	v_cndmask_b32_e64 v44, v52, v45, s[40:41]
	v_mov_b32_e32 v45, v3
	v_pk_mul_f32 v[44:45], v[44:45], v[204:205]
	s_nop 1
	v_mov_b32_dpp v21, v45 row_shr:4 row_mask:0xf bank_mask:0xa
	v_mov_b32_dpp v21, v45 row_shl:4 row_mask:0xf bank_mask:0x5
	v_cndmask_b32_e64 v43, v44, v44, s[40:41]
	v_cvt_pk_bf16_f32 v42, v42, v9
	v_mov_b32_e32 v9, v161
	s_waitcnt lgkmcnt(0)
	v_mul_f32_e32 v21, v23, v21
	v_cndmask_b32_e64 v21, v21, -v21, s[36:37]
	v_fmac_f32_e32 v21, v19, v45
	v_cndmask_b32_e64 v21, v21, v45, s[40:41]
	v_mul_f32_e32 v21, 0x3e38aa3b, v21
	v_cvt_pk_bf16_f32 v43, v43, v21
	v_lshl_add_u64 v[44:45], v[32:33], 0, v[8:9]
	global_store_dwordx2 v[44:45], v[42:43], off offset:512
	v_and_b32_e32 v45, 0xffff0000, v37
	v_and_b32_e32 v44, 0xffff0000, v36
	v_lshlrev_b32_e32 v43, 16, v37
	v_lshlrev_b32_e32 v42, 16, v36
	v_pk_mul_f32 v[36:37], v[44:45], v[44:45]
	s_nop 0
	v_pk_fma_f32 v[36:37], v[42:43], v[42:43], v[36:37]
	s_nop 0
	v_add_f32_e32 v9, v36, v37
	s_nop 1
	v_add_f32_dpp v9, v9, v9 quad_perm:[1,0,3,2] row_mask:0xf bank_mask:0xf bound_ctrl:1
	s_nop 1
	v_add_f32_dpp v9, v9, v9 quad_perm:[2,3,0,1] row_mask:0xf bank_mask:0xf bound_ctrl:1
	s_nop 1
	v_add_f32_dpp v9, v9, v9 row_ror:4 row_mask:0xf bank_mask:0xf bound_ctrl:1
	s_nop 1
	v_add_f32_dpp v9, v9, v9 row_ror:8 row_mask:0xf bank_mask:0xf bound_ctrl:1
	v_fmamk_f32 v9, v9, 0x3c800000, v237
	v_rsq_f32_e32 v9, v9
	s_nop 0
	v_mul_f32_e32 v21, v9, v42
	v_mul_f32_e32 v21, v4, v21
	s_nop 1
	v_mov_b32_dpp v36, v21 row_shr:4 row_mask:0xf bank_mask:0xa
	v_mov_b32_dpp v36, v21 row_shl:4 row_mask:0xf bank_mask:0x5
	s_waitcnt lgkmcnt(0)
	v_mul_f32_e32 v36, v51, v36
	v_cndmask_b32_e64 v36, v36, -v36, s[36:37]
	v_fmac_f32_e32 v36, v50, v21
	v_cndmask_b32_e64 v21, v36, v21, s[40:41]
	v_mul_f32_e32 v36, v9, v44
	v_mul_f32_e32 v36, v5, v36
	s_nop 1
	v_mov_b32_dpp v37, v36 row_shr:4 row_mask:0xf bank_mask:0xa
	v_mov_b32_dpp v37, v36 row_shl:4 row_mask:0xf bank_mask:0x5
	s_waitcnt lgkmcnt(0)
	v_mul_f32_e32 v37, v49, v37
	v_cndmask_b32_e64 v37, v37, -v37, s[36:37]
	v_fmac_f32_e32 v37, v48, v36
	v_cndmask_b32_e64 v36, v37, v36, s[40:41]
	v_mul_f32_e32 v37, v9, v43
	v_mul_f32_e32 v37, v6, v37
	s_nop 1
	v_mov_b32_dpp v42, v37 row_shr:4 row_mask:0xf bank_mask:0xa
	v_mov_b32_dpp v42, v37 row_shl:4 row_mask:0xf bank_mask:0x5
	v_mul_f32_e32 v9, v9, v45
	v_mul_f32_e32 v9, v7, v9
	s_waitcnt lgkmcnt(0)
	v_mul_f32_e32 v42, v47, v42
	v_cndmask_b32_e64 v42, v42, -v42, s[36:37]
	v_fmac_f32_e32 v42, v46, v37
	v_cndmask_b32_e64 v37, v42, v37, s[40:41]
	s_nop 1
	v_mov_b32_dpp v42, v9 row_shr:4 row_mask:0xf bank_mask:0xa
	v_mov_b32_dpp v42, v9 row_shl:4 row_mask:0xf bank_mask:0x5
	s_waitcnt lgkmcnt(0)
	v_mul_f32_e32 v23, v23, v42
	v_cndmask_b32_e64 v23, v23, -v23, s[36:37]
	v_fmac_f32_e32 v23, v19, v9
	v_cndmask_b32_e64 v9, v23, v9, s[40:41]
	s_and_saveexec_b64 s[0:1], vcc
	s_cbranch_execz .LBB0_533
	v_mov_b32_e32 v23, v161
	v_cvt_pk_bf16_f32 v36, v21, v36
	v_cvt_pk_bf16_f32 v37, v37, v9
	v_lshl_add_u64 v[32:33], v[32:33], 0, v[22:23]
	global_store_dwordx2 v[32:33], v[36:37], off offset:512
	s_branch .LBB0_533
